# diff attention: LDS-DMA (K x3/V x2), QK of tile t+1 computed in iteration t after softmax-scale of tile t (score regs free of MFMA drain wait)
# speedup vs baseline: 1.0008x; 1.0008x over previous
.LBB0_356:
	s_or_b64 exec, exec, s[0:1]
	v_readlane_b32 s0, v255, 49
	v_readlane_b32 s1, v255, 50
	v_ashrrev_i32_e32 v5, 6, v2
	v_lshl_add_u32 v2, v2, 2, 0
	v_lshlrev_b32_e32 v6, 5, v5
	v_and_b32_e32 v4, 63, v0
	v_add_u32_e32 v2, 0x20100, v2
	global_load_dword v177, v1, s[0:1]
	s_lshl_b32 s0, s16, 9
	v_lshl_add_u32 v7, s19, 8, v6
	s_and_b32 s4, s0, 0x3000
	s_waitcnt vmcnt(1)
	ds_write_b32 v2, v3
	v_add_u32_e32 v179, s4, v7
	v_lshlrev_b32_e32 v2, 13, v5
	v_lshlrev_b32_e32 v3, 2, v4
	v_and_or_b32 v8, v0, 31, v179
	v_add3_u32 v228, 0, v2, v3
	v_add_u32_e32 v228, 0x2400, v228
	v_mov_b64_e32 v[2:3], s[88:89]
	s_lshl_b32 s21, s19, 2
	v_mad_i64_i32 v[2:3], s[0:1], v8, s87, v[2:3]
	s_add_i32 s22, s21, 4
	s_lshl_b32 s20, s18, 7
	s_lshl_b32 s94, s18, 8
	s_mul_i32 s0, s4, 0x9000
	s_add_u32 s0, s88, s0
	s_addc_u32 s1, s89, 0
	s_add_u32 s23, s0, s94
	s_addc_u32 s24, s1, 0
	s_lshl_b32 s0, s18, 22
	v_readlane_b32 s1, v255, 47
	s_add_u32 s0, s1, s0
	v_readlane_b32 s1, v255, 48
	s_addc_u32 s1, s1, 0
	s_lshl_b32 s4, s4, 1
	v_lshrrev_b32_e32 v0, 1, v0
	s_add_u32 s6, s0, s4
	v_lshl_add_u64 v[2:3], v[2:3], 0, s[94:95]
	v_and_b32_e32 v0, 16, v0
	s_addc_u32 s7, s1, 0
	s_lshl_b32 s0, s17, 8
	v_lshl_add_u64 v[166:167], v[2:3], 0, v[0:1]
	v_subrev_u32_e32 v0, s0, v6
	v_or_b32_e32 v229, 31, v7
	s_or_b32 s25, s21, 2
	v_add_u32_e32 v230, 0xe41, v0
	s_mov_b64 s[0:1], 0
	s_mov_b64 s[8:9], -1
	s_branch .LBB0_358

.LBB0_358:
	s_lshl_b64 s[0:1], s[0:1], 1
	v_lshl_add_u64 v[2:3], v[166:167], 0, s[0:1]
	global_load_dwordx4 v[98:101], v[2:3], off
	global_load_dwordx4 v[102:105], v[2:3], off offset:32
	global_load_dwordx4 v[106:109], v[2:3], off offset:64
	global_load_dwordx4 v[110:113], v[2:3], off offset:96
	v_mbcnt_lo_u32_b32 v28, -1, 0
	v_mbcnt_hi_u32_b32 v28, -1, v28
	s_xor_b64 s[8:9], s[8:9], -1
	v_add_u32_e32 v12, s83, v28
	v_ashrrev_i32_e32 v0, 31, v12
	v_lshrrev_b32_e32 v0, 29, v0
	v_add_u32_e32 v0, v12, v0
	v_ashrrev_i32_e32 v231, 3, v0
	v_and_b32_e32 v0, -8, v0
	v_sub_u32_e32 v29, v12, v0
	v_lshlrev_b32_e32 v2, 3, v29
	v_ashrrev_i32_e32 v16, 3, v12
	v_add_u32_e32 v12, 0x200, v12
	s_add_u32 s0, s23, s0
	v_ashrrev_i32_e32 v3, 31, v2
	v_lshlrev_b32_e32 v0, 4, v28
	v_ashrrev_i32_e32 v20, 3, v12
	s_addc_u32 s1, s24, s1
	v_lshlrev_b64 v[2:3], 1, v[2:3]
	v_and_b32_e32 v0, 0x70, v0
	v_ashrrev_i32_e32 v17, 31, v16
	v_ashrrev_i32_e32 v21, 31, v20
	v_lshl_add_u64 v[168:169], s[0:1], 0, v[2:3]
	v_lshl_add_u64 v[170:171], s[6:7], 0, v[0:1]
	v_lshlrev_b64 v[172:173], 15, v[16:17]
	v_lshlrev_b64 v[174:175], 15, v[20:21]
	s_mov_b32 s98, 0x1c71c71d
	v_mov_b32_e32 v245, 0x240000
	v_mov_b32_e32 v252, 0x80
	s_add_i32 s99, s83, 0
	v_add_u32_e32 v6, s99, v28
	v_mul_hi_u32 v7, v6, s98
	v_mul_u32_u24_e32 v8, 9, v7
	v_sub_u32_e32 v8, v6, v8
	v_min_u32_e32 v8, 7, v8
	v_lshlrev_b32_e32 v12, 4, v8
	v_mov_b32_e32 v13, 0
	v_add_u32_e32 v12, 0x800, v12
	v_mov_b32_e32 v9, 0x9000
	v_mad_u64_u32 v[10:11], s[100:101], v7, v9, v[12:13]
	v_lshl_add_u64 v[222:223], s[0:1], 0, v[10:11]
	s_add_i32 s99, s83, 512
	v_add_u32_e32 v6, s99, v28
	v_mul_hi_u32 v7, v6, s98
	v_mul_u32_u24_e32 v8, 9, v7
	v_sub_u32_e32 v8, v6, v8
	v_min_u32_e32 v8, 7, v8
	v_lshlrev_b32_e32 v12, 4, v8
	v_mov_b32_e32 v13, 0
	v_add_u32_e32 v12, 0x800, v12
	v_mov_b32_e32 v9, 0x9000
	v_mad_u64_u32 v[10:11], s[100:101], v7, v9, v[12:13]
	v_lshl_add_u64 v[224:225], s[0:1], 0, v[10:11]
	s_add_i32 s99, s83, 0
	v_add_u32_e32 v6, s99, v28
	v_mul_hi_u32 v7, v6, s98
	v_mul_u32_u24_e32 v8, 9, v7
	v_sub_u32_e32 v8, v6, v8
	v_min_u32_e32 v8, 7, v8
	v_lshlrev_b32_e32 v12, 4, v8
	v_mov_b32_e32 v13, 0
	v_mov_b32_e32 v9, 0x8000
	v_mad_u64_u32 v[10:11], s[100:101], v7, v9, v[12:13]
	v_lshl_add_u64 v[226:227], s[6:7], 0, v[10:11]
	s_add_i32 s99, s83, 512
	v_add_u32_e32 v6, s99, v28
	v_mul_hi_u32 v7, v6, s98
	v_mul_u32_u24_e32 v8, 9, v7
	v_sub_u32_e32 v8, v6, v8
	v_min_u32_e32 v8, 7, v8
	v_lshlrev_b32_e32 v12, 4, v8
	v_mov_b32_e32 v13, 0
	v_mov_b32_e32 v9, 0x8000
	v_mad_u64_u32 v[10:11], s[100:101], v7, v9, v[12:13]
	v_lshl_add_u64 v[248:249], s[6:7], 0, v[10:11]
	s_add_i32 s99, s83, 1024
	v_add_u32_e32 v6, s99, v28
	v_mul_hi_u32 v7, v6, s98
	v_mul_u32_u24_e32 v8, 9, v7
	v_sub_u32_e32 v8, v6, v8
	v_min_u32_e32 v8, 7, v8
	v_lshlrev_b32_e32 v12, 4, v8
	v_mov_b32_e32 v13, 0
	v_mov_b32_e32 v9, 0x8000
	v_mad_u64_u32 v[10:11], s[100:101], v7, v9, v[12:13]
	v_lshl_add_u64 v[250:251], s[6:7], 0, v[10:11]
	s_mov_b32 s101, 0
	s_bitcmp1_b32 s101, 0
	s_mov_b32 s98, 0x6c00
	s_cselect_b32 s98, 0xb400, s98
	s_lshl_b32 m0, s83, 4
	s_add_i32 s98, s98, m0
	v_mad_u64_u32 v[204:205], vcc, v252, s101, v[226:227]
	s_mov_b32 m0, s98
	v_mad_u64_u32 v[206:207], vcc, v252, s101, v[248:249]
	global_load_lds_dwordx4 v[204:205], off
	s_add_i32 m0, s98, 0x2000
	s_cmp_ge_u32 s83, 0x80
	global_load_lds_dwordx4 v[206:207], off
	s_cbranch_scc1 .Lpk_p0
	v_mad_u64_u32 v[208:209], vcc, v252, s101, v[250:251]
	s_add_i32 m0, s98, 0x4000
	s_nop 0
	global_load_lds_dwordx4 v[208:209], off
.Lpk_p0:
	s_lshl_b32 m0, s83, 4
	s_add_i32 s98, m0, 0x0
	v_mad_u64_u32 v[204:205], vcc, v245, s101, v[222:223]
	s_mov_b32 m0, s98
	s_cmp_lg_u32 s83, 0
	global_load_lds_dwordx4 v[204:205], off
	s_cbranch_scc1 .Lpk_p1
	v_mad_u64_u32 v[206:207], vcc, v245, s101, v[224:225]
	s_add_i32 m0, s98, 0x2000
	s_nop 0
	global_load_lds_dwordx4 v[206:207], off
.Lpk_p1:
	s_mov_b32 s101, 1
	s_lshl_b32 m0, s83, 4
	s_add_i32 s98, m0, 0x2400
	v_mad_u64_u32 v[204:205], vcc, v245, s101, v[222:223]
	s_mov_b32 m0, s98
	s_cmp_lg_u32 s83, 0
	global_load_lds_dwordx4 v[204:205], off
	s_cbranch_scc1 .Lpk_p2
	v_mad_u64_u32 v[206:207], vcc, v245, s101, v[224:225]
	s_add_i32 m0, s98, 0x2000
	s_nop 0
	global_load_lds_dwordx4 v[206:207], off
.Lpk_p2:
	v_add_u32_e32 v17, 64, v231
	v_mad_i64_i32 v[4:5], s[4:5], v231, s87, v[168:169]
	v_lshl_add_u64 v[18:19], v[170:171], 0, v[172:173]
	v_lshl_add_u64 v[22:23], v[170:171], 0, v[174:175]
	v_mad_i64_i32 v[24:25], s[4:5], v17, s87, v[168:169]
	v_add_u32_e32 v17, 0x80, v231
	s_nop 0
	v_mad_i64_i32 v[26:27], s[4:5], v17, s87, v[168:169]
	v_add_u32_e32 v17, 0xc0, v231
	v_mov_b64_e32 v[18:19], s[0:1]
	v_mad_i64_i32 v[18:19], s[0:1], v17, s87, v[18:19]
	v_lshl_add_u64 v[2:3], v[18:19], 0, v[2:3]
	v_lshl_add_u64 v[18:19], s[6:7], 0, v[172:173]
	v_lshl_add_u64 v[18:19], v[18:19], 0, v[0:1]
	v_lshl_add_u64 v[22:23], s[6:7], 0, v[174:175]
	v_lshl_add_u64 v[22:23], v[22:23], 0, v[0:1]
	v_lshlrev_b32_e32 v18, 1, v28
	v_lshrrev_b32_e32 v19, 1, v28
	v_and_b32_e32 v22, 19, v28
	v_and_b32_e32 v18, 8, v18
	v_and_b32_e32 v19, 4, v19
	v_add_u32_e32 v234, 0, v0
	v_or3_b32 v0, v18, v22, v19
	v_mul_lo_u32 v237, v20, s86
	v_mul_lo_u32 v19, v231, s86
	v_lshlrev_b32_e32 v20, 4, v29
	v_mov_b32_e32 v17, s77
	v_mul_lo_u32 v235, v16, s86
	v_add3_u32 v239, 0, v19, v20
	v_bfe_u32 v23, v28, 5, 1
	v_add_u32_e32 v16, v234, v235
	v_add_u32_e32 v18, v234, v237
	v_and_b32_e32 v21, 31, v28
	v_lshlrev_b32_e32 v232, 4, v23
	v_lshlrev_b32_e32 v23, 3, v23
	v_mov_b32_e32 v2, v1
	v_mov_b32_e32 v3, v1
	v_mul_u32_u24_e32 v233, 0x90, v21
	v_sub_u32_e32 v236, v21, v23
	v_mul_u32_u24_e32 v238, 0x90, v0
	v_mov_b32_e32 v0, v1
	s_mov_b32 s94, 0
	v_mov_b32_e32 v178, 0
	v_mov_b32_e32 v240, v230
	v_mov_b32_e32 v241, 0
	s_mov_b32 s26, s94
	s_waitcnt vmcnt(0) lgkmcnt(0)
	s_barrier
	ds_read_b32 v176, v17
	v_mov_b32_e32 v14, v1
	v_mov_b32_e32 v15, v1
	v_mov_b32_e32 v4, v1
	v_mov_b32_e32 v5, v1
	v_mov_b32_e32 v6, v1
	v_mov_b32_e32 v7, v1
	v_mov_b32_e32 v8, v1
	v_mov_b32_e32 v9, v1
	v_mov_b32_e32 v10, v1
	v_mov_b32_e32 v11, v1
	v_mov_b32_e32 v12, v1
	v_mov_b32_e32 v13, v1
	v_mov_b64_e32 v[64:65], v[14:15]
	v_mov_b64_e32 v[48:49], v[14:15]
	v_mov_b64_e32 v[32:33], v[14:15]
	v_mov_b64_e32 v[62:63], v[12:13]
	v_mov_b64_e32 v[60:61], v[10:11]
	v_mov_b64_e32 v[58:59], v[8:9]
	v_mov_b64_e32 v[56:57], v[6:7]
	v_mov_b64_e32 v[54:55], v[4:5]
	v_mov_b64_e32 v[52:53], v[2:3]
	v_mov_b64_e32 v[50:51], v[0:1]
	v_mov_b64_e32 v[46:47], v[12:13]
	v_mov_b64_e32 v[44:45], v[10:11]
	v_mov_b64_e32 v[42:43], v[8:9]
	v_mov_b64_e32 v[40:41], v[6:7]
	v_mov_b64_e32 v[38:39], v[4:5]
	v_mov_b64_e32 v[36:37], v[2:3]
	v_mov_b64_e32 v[34:35], v[0:1]
	v_mov_b64_e32 v[30:31], v[12:13]
	v_mov_b64_e32 v[28:29], v[10:11]
	v_mov_b64_e32 v[26:27], v[8:9]
	v_mov_b64_e32 v[24:25], v[6:7]
	v_mov_b64_e32 v[22:23], v[4:5]
	v_mov_b64_e32 v[20:21], v[2:3]
	v_mov_b64_e32 v[18:19], v[0:1]
	v_mov_b64_e32 v[16:17], v[14:15]
	v_mov_b64_e32 v[14:15], v[12:13]
	v_mov_b64_e32 v[12:13], v[10:11]
	v_mov_b64_e32 v[10:11], v[8:9]
	v_mov_b64_e32 v[8:9], v[6:7]
	v_mov_b64_e32 v[6:7], v[4:5]
	v_mov_b64_e32 v[4:5], v[2:3]
	v_mov_b64_e32 v[2:3], v[0:1]
	s_mov_b32 s99, 0x0
	v_add3_u32 v148, v232, v238, s99
	ds_read_b128 v[114:117], v148
	ds_read_b128 v[118:121], v148 offset:4608
	ds_read_b128 v[122:125], v148 offset:32
	ds_read_b128 v[126:129], v148 offset:4640
	ds_read_b128 v[130:133], v148 offset:64
	ds_read_b128 v[134:137], v148 offset:4672
	ds_read_b128 v[138:141], v148 offset:96
	ds_read_b128 v[142:145], v148 offset:4704
	s_waitcnt lgkmcnt(7)
	v_mfma_f32_32x32x16_bf16 v[82:97], v[114:117], v[98:101], 0
	s_waitcnt lgkmcnt(6)
	v_mfma_f32_32x32x16_bf16 v[66:81], v[118:121], v[98:101], 0
	s_waitcnt lgkmcnt(5)
	v_mfma_f32_32x32x16_bf16 v[82:97], v[122:125], v[102:105], v[82:97]
	s_waitcnt lgkmcnt(4)
	v_mfma_f32_32x32x16_bf16 v[66:81], v[126:129], v[102:105], v[66:81]
	s_waitcnt lgkmcnt(3)
	v_mfma_f32_32x32x16_bf16 v[82:97], v[130:133], v[106:109], v[82:97]
	s_waitcnt lgkmcnt(2)
	v_mfma_f32_32x32x16_bf16 v[66:81], v[134:137], v[106:109], v[66:81]
	s_waitcnt lgkmcnt(1)
	v_mfma_f32_32x32x16_bf16 v[82:97], v[138:141], v[110:113], v[82:97]
	s_waitcnt lgkmcnt(0)
	v_mfma_f32_32x32x16_bf16 v[66:81], v[142:145], v[110:113], v[66:81]
.Lqn_skipp:
.LBB0_359:
	s_add_i32 s27, s26, 1
	s_cmp_lt_u32 s27, s22
	s_cselect_b64 s[10:11], -1, 0
	s_cmp_ge_u32 s27, s22
	s_cbranch_scc1 .LBB0_362
	s_bitcmp1_b32 s27, 0
	s_mov_b32 s98, 0x6c00
	s_cselect_b32 s98, 0xb400, s98
	s_lshl_b32 m0, s83, 4
	s_add_i32 s98, s98, m0
	v_mad_u64_u32 v[204:205], vcc, v252, s27, v[226:227]
	s_mov_b32 m0, s98
	v_mad_u64_u32 v[206:207], vcc, v252, s27, v[248:249]
	global_load_lds_dwordx4 v[204:205], off
	s_add_i32 m0, s98, 0x2000
	s_cmp_ge_u32 s83, 0x80
	global_load_lds_dwordx4 v[206:207], off
	s_cbranch_scc1 .Lpk_k1
	v_mad_u64_u32 v[208:209], vcc, v252, s27, v[250:251]
	s_add_i32 m0, s98, 0x4000
	s_nop 0
	global_load_lds_dwordx4 v[208:209], off
.Lpk_k1:
	s_add_i32 s100, s26, 2
	s_cmp_ge_u32 s100, s22
	s_cbranch_scc1 .LBB0_362
	s_lshl_b32 m0, s83, 4
	s_add_i32 s98, m0, 0x4800
	v_mad_u64_u32 v[204:205], vcc, v245, s100, v[222:223]
	s_mov_b32 m0, s98
	s_cmp_lg_u32 s83, 0
	global_load_lds_dwordx4 v[204:205], off
	s_cbranch_scc1 .LBB0_362
	v_mad_u64_u32 v[206:207], vcc, v245, s100, v[224:225]
	s_add_i32 m0, s98, 0x2000
	s_nop 0
	global_load_lds_dwordx4 v[206:207], off
.LBB0_362:
	v_cmp_le_i32_e32 vcc, s94, v229
	s_and_saveexec_b64 s[12:13], vcc
	s_cbranch_execz .LBB0_372
	s_mov_b32 s99, 0x4800
	s_bitcmp1_b32 s26, 0
	s_cselect_b32 s99, 0x9000, s99
	v_add3_u32 v242, v232, v233, s99
	ds_read_b128 v[162:165], v242 offset:9216
	ds_read_b128 v[158:161], v242 offset:13824
	ds_read_b128 v[154:157], v242 offset:18432
	ds_read_b128 v[150:153], v242 offset:23040
	s_movk_i32 s0, 0xbf
	v_add_u32_e32 v180, 0x80, v240
	v_add3_u32 v0, v236, v240, s0
	v_cmp_gt_i32_e32 vcc, s85, v180
	s_and_saveexec_b64 s[0:1], vcc
	s_xor_b64 s[0:1], exec, s[0:1]
	s_cbranch_execz .LBB0_365
	v_add_u32_e32 v181, -1, v0
	v_add_u32_e32 v182, 0x1fe, v0
	v_add_u32_e32 v183, 0x1fd, v0
	v_add_u32_e32 v184, 0x1fc, v0
	v_add_u32_e32 v185, 0x1fb, v0
	v_add_u32_e32 v186, 0x1fa, v0
	v_add_u32_e32 v187, 0x1f9, v0
	v_and_b32_e32 v180, 0x1ff, v0
	s_add_i32 s4, 0, 0x20100
	v_and_b32_e32 v181, 0x1ff, v181
	v_and_b32_e32 v182, 0x1ff, v182
	v_and_b32_e32 v183, 0x1ff, v183
	v_and_b32_e32 v184, 0x1ff, v184
	v_and_b32_e32 v185, 0x1ff, v185
	v_and_b32_e32 v186, 0x1ff, v186
	v_and_b32_e32 v187, 0x1ff, v187
	v_lshl_add_u32 v180, v180, 2, s4
	v_lshl_add_u32 v181, v181, 2, s4
	v_lshl_add_u32 v182, v182, 2, s4
	v_lshl_add_u32 v183, v183, 2, s4
	v_lshl_add_u32 v184, v184, 2, s4
	v_lshl_add_u32 v185, v185, 2, s4
	v_lshl_add_u32 v186, v186, 2, s4
	v_lshl_add_u32 v187, v187, 2, s4
	ds_read_b32 v180, v180
	ds_read_b32 v181, v181
	ds_read_b32 v182, v182
	ds_read_b32 v183, v183
	ds_read_b32 v184, v184
	ds_read_b32 v185, v185
	ds_read_b32 v186, v186
	ds_read_b32 v187, v187
	s_waitcnt lgkmcnt(6)
	v_pk_add_f32 v[180:181], v[180:181], v[178:179] op_sel_hi:[1,0] neg_lo:[0,1] neg_hi:[0,1]
	s_nop 0
	v_pk_fma_f32 v[180:181], v[82:83], s[82:83], v[180:181] op_sel_hi:[1,0,1]
	s_waitcnt lgkmcnt(4)
	v_pk_add_f32 v[82:83], v[182:183], v[178:179] op_sel_hi:[1,0] neg_lo:[0,1] neg_hi:[0,1]
	v_max3_f32 v188, v180, s33, v181
	v_pk_fma_f32 v[182:183], v[84:85], s[82:83], v[82:83] op_sel_hi:[1,0,1]
	s_waitcnt lgkmcnt(2)
	v_pk_add_f32 v[82:83], v[184:185], v[178:179] op_sel_hi:[1,0] neg_lo:[0,1] neg_hi:[0,1]
	v_max3_f32 v84, v188, v182, v183
	v_pk_fma_f32 v[184:185], v[86:87], s[82:83], v[82:83] op_sel_hi:[1,0,1]
	s_waitcnt lgkmcnt(0)
	v_pk_add_f32 v[82:83], v[186:187], v[178:179] op_sel_hi:[1,0] neg_lo:[0,1] neg_hi:[0,1]
	v_max3_f32 v84, v84, v184, v185
	v_pk_fma_f32 v[186:187], v[88:89], s[82:83], v[82:83] op_sel_hi:[1,0,1]
	v_add_u32_e32 v82, 0x1f0, v0
	v_max3_f32 v188, v84, v186, v187
	v_add_u32_e32 v83, 0x1ef, v0
	v_add_u32_e32 v84, 0x1ee, v0
	v_add_u32_e32 v85, 0x1ed, v0
	v_add_u32_e32 v86, 0x1ec, v0
	v_add_u32_e32 v87, 0x1eb, v0
	v_add_u32_e32 v88, 0x1ea, v0
	v_add_u32_e32 v89, 0x1e9, v0
	v_and_b32_e32 v82, 0x1ff, v82
	v_and_b32_e32 v83, 0x1ff, v83
	v_and_b32_e32 v84, 0x1ff, v84
	v_and_b32_e32 v85, 0x1ff, v85
	v_and_b32_e32 v86, 0x1ff, v86
	v_and_b32_e32 v87, 0x1ff, v87
	v_and_b32_e32 v88, 0x1ff, v88
	v_and_b32_e32 v89, 0x1ff, v89
	v_lshl_add_u32 v82, v82, 2, s4
	v_lshl_add_u32 v83, v83, 2, s4
	v_lshl_add_u32 v84, v84, 2, s4
	v_lshl_add_u32 v85, v85, 2, s4
	v_lshl_add_u32 v86, v86, 2, s4
	v_lshl_add_u32 v87, v87, 2, s4
	v_lshl_add_u32 v88, v88, 2, s4
	v_lshl_add_u32 v89, v89, 2, s4
	ds_read_b32 v82, v82
	ds_read_b32 v83, v83
	ds_read_b32 v84, v84
	ds_read_b32 v85, v85
	ds_read_b32 v86, v86
	ds_read_b32 v87, v87
	ds_read_b32 v88, v88
	ds_read_b32 v89, v89
	s_waitcnt lgkmcnt(6)
	v_pk_add_f32 v[82:83], v[82:83], v[178:179] op_sel_hi:[1,0] neg_lo:[0,1] neg_hi:[0,1]
	s_nop 0
	v_pk_fma_f32 v[192:193], v[90:91], s[82:83], v[82:83] op_sel_hi:[1,0,1]
	s_waitcnt lgkmcnt(4)
	v_pk_add_f32 v[82:83], v[84:85], v[178:179] op_sel_hi:[1,0] neg_lo:[0,1] neg_hi:[0,1]
	v_max3_f32 v90, v188, v192, v193
	v_pk_fma_f32 v[206:207], v[92:93], s[82:83], v[82:83] op_sel_hi:[1,0,1]
	s_waitcnt lgkmcnt(2)
	v_pk_add_f32 v[82:83], v[86:87], v[178:179] op_sel_hi:[1,0] neg_lo:[0,1] neg_hi:[0,1]
	v_max3_f32 v84, v90, v206, v207
	v_pk_fma_f32 v[188:189], v[94:95], s[82:83], v[82:83] op_sel_hi:[1,0,1]
	s_waitcnt lgkmcnt(0)
	v_pk_add_f32 v[82:83], v[88:89], v[178:179] op_sel_hi:[1,0] neg_lo:[0,1] neg_hi:[0,1]
	v_max3_f32 v84, v84, v188, v189
	v_pk_fma_f32 v[190:191], v[96:97], s[82:83], v[82:83] op_sel_hi:[1,0,1]
	v_add_u32_e32 v82, 0x1e0, v0
	v_max3_f32 v90, v84, v190, v191
	v_add_u32_e32 v83, 0x1df, v0
	v_add_u32_e32 v84, 0x1de, v0
	v_add_u32_e32 v85, 0x1dd, v0
	v_add_u32_e32 v86, 0x1dc, v0
	v_add_u32_e32 v87, 0x1db, v0
	v_add_u32_e32 v88, 0x1da, v0
	v_add_u32_e32 v89, 0x1d9, v0
	v_and_b32_e32 v82, 0x1ff, v82
	v_and_b32_e32 v83, 0x1ff, v83
	v_and_b32_e32 v84, 0x1ff, v84
	v_and_b32_e32 v85, 0x1ff, v85
	v_and_b32_e32 v86, 0x1ff, v86
	v_and_b32_e32 v87, 0x1ff, v87
	v_and_b32_e32 v88, 0x1ff, v88
	v_and_b32_e32 v89, 0x1ff, v89
	v_lshl_add_u32 v82, v82, 2, s4
	v_lshl_add_u32 v83, v83, 2, s4
	v_lshl_add_u32 v84, v84, 2, s4
	v_lshl_add_u32 v85, v85, 2, s4
	v_lshl_add_u32 v86, v86, 2, s4
	v_lshl_add_u32 v87, v87, 2, s4
	v_lshl_add_u32 v88, v88, 2, s4
	v_lshl_add_u32 v89, v89, 2, s4
	ds_read_b32 v82, v82
	ds_read_b32 v83, v83
	ds_read_b32 v84, v84
	ds_read_b32 v85, v85
	ds_read_b32 v86, v86
	ds_read_b32 v87, v87
	ds_read_b32 v88, v88
	ds_read_b32 v89, v89
	s_waitcnt lgkmcnt(6)
	v_pk_add_f32 v[82:83], v[82:83], v[178:179] op_sel_hi:[1,0] neg_lo:[0,1] neg_hi:[0,1]
	s_nop 0
	v_pk_fma_f32 v[204:205], v[66:67], s[82:83], v[82:83] op_sel_hi:[1,0,1]
	s_waitcnt lgkmcnt(4)
	v_pk_add_f32 v[66:67], v[84:85], v[178:179] op_sel_hi:[1,0] neg_lo:[0,1] neg_hi:[0,1]
	v_max3_f32 v82, v90, v204, v205
	v_pk_fma_f32 v[208:209], v[68:69], s[82:83], v[66:67] op_sel_hi:[1,0,1]
	s_waitcnt lgkmcnt(2)
	v_pk_add_f32 v[66:67], v[86:87], v[178:179] op_sel_hi:[1,0] neg_lo:[0,1] neg_hi:[0,1]
	v_max3_f32 v68, v82, v208, v209
	v_pk_fma_f32 v[210:211], v[70:71], s[82:83], v[66:67] op_sel_hi:[1,0,1]
	s_waitcnt lgkmcnt(0)
	v_pk_add_f32 v[66:67], v[88:89], v[178:179] op_sel_hi:[1,0] neg_lo:[0,1] neg_hi:[0,1]
	v_max3_f32 v68, v68, v210, v211
	v_pk_fma_f32 v[212:213], v[72:73], s[82:83], v[66:67] op_sel_hi:[1,0,1]
	v_add_u32_e32 v66, 0x1d0, v0
	v_max3_f32 v82, v68, v212, v213
	v_add_u32_e32 v67, 0x1cf, v0
	v_add_u32_e32 v68, 0x1ce, v0
	v_add_u32_e32 v69, 0x1cd, v0
	v_add_u32_e32 v70, 0x1cc, v0
	v_add_u32_e32 v71, 0x1cb, v0
	v_add_u32_e32 v72, 0x1ca, v0
	v_and_b32_e32 v66, 0x1ff, v66
	v_and_b32_e32 v67, 0x1ff, v67
	v_and_b32_e32 v68, 0x1ff, v68
	v_and_b32_e32 v69, 0x1ff, v69
	v_and_b32_e32 v70, 0x1ff, v70
	v_and_b32_e32 v71, 0x1ff, v71
	v_and_b32_e32 v72, 0x1ff, v72
	v_add_u32_e32 v0, 0x1c9, v0
	v_lshl_add_u32 v66, v66, 2, s4
	v_lshl_add_u32 v67, v67, 2, s4
	v_lshl_add_u32 v68, v68, 2, s4
	v_lshl_add_u32 v69, v69, 2, s4
	v_lshl_add_u32 v70, v70, 2, s4
	v_lshl_add_u32 v71, v71, 2, s4
	v_lshl_add_u32 v72, v72, 2, s4
	v_and_b32_e32 v0, 0x1ff, v0
	v_lshl_add_u32 v0, v0, 2, s4
	ds_read_b32 v66, v66
	ds_read_b32 v67, v67
	ds_read_b32 v68, v68
	ds_read_b32 v69, v69
	ds_read_b32 v70, v70
	ds_read_b32 v71, v71
	ds_read_b32 v72, v72
	ds_read_b32 v73, v0
	s_waitcnt lgkmcnt(6)
	v_pk_add_f32 v[66:67], v[66:67], v[178:179] op_sel_hi:[1,0] neg_lo:[0,1] neg_hi:[0,1]
	s_nop 0
	v_pk_fma_f32 v[214:215], v[74:75], s[82:83], v[66:67] op_sel_hi:[1,0,1]
	s_waitcnt lgkmcnt(4)
	v_pk_add_f32 v[66:67], v[68:69], v[178:179] op_sel_hi:[1,0] neg_lo:[0,1] neg_hi:[0,1]
	v_max3_f32 v0, v82, v214, v215
	v_pk_fma_f32 v[216:217], v[76:77], s[82:83], v[66:67] op_sel_hi:[1,0,1]
	s_waitcnt lgkmcnt(2)
	v_pk_add_f32 v[66:67], v[70:71], v[178:179] op_sel_hi:[1,0] neg_lo:[0,1] neg_hi:[0,1]
	v_max3_f32 v0, v0, v216, v217
	v_pk_fma_f32 v[218:219], v[78:79], s[82:83], v[66:67] op_sel_hi:[1,0,1]
	s_waitcnt lgkmcnt(0)
	v_pk_add_f32 v[66:67], v[72:73], v[178:179] op_sel_hi:[1,0] neg_lo:[0,1] neg_hi:[0,1]
	v_max3_f32 v0, v0, v218, v219
	v_pk_fma_f32 v[220:221], v[80:81], s[82:83], v[66:67] op_sel_hi:[1,0,1]
	s_nop 0
	v_max3_f32 v243, v0, v220, v221

.LBB0_369:
	s_andn2_b64 vcc, exec, s[14:15]
	v_mov_b32_e32 v0, 1.0
	s_cbranch_vccnz .LBB0_371
	v_mov_b32_e32 v0, v243
	v_mov_b32_e32 v146, v243
	s_nop 1
	v_permlane32_swap_b32_e32 v0, v146
	v_cmp_eq_u32_e32 vcc, v0, v243
	s_nop 1
	v_cndmask_b32_e32 v0, v0, v146, vcc
	v_max_f32_e32 v0, v0, v0
	v_max_f32_e32 v146, v243, v243
	v_max_f32_e32 v0, v146, v0
	v_cmp_lt_f32_e32 vcc, s92, v0
	s_or_b64 vcc, s[0:1], vcc
	s_nop 0
	v_cndmask_b32_e32 v146, 0, v0, vcc
	v_exp_f32_e64 v0, -v146
	v_add_f32_e32 v178, v178, v146
	v_sub_f32_e32 v180, v180, v146
	v_sub_f32_e32 v181, v181, v146
	v_cndmask_b32_e64 v0, v0, 1.0, s[0:1]
	v_pk_mul_f32 v[64:65], v[64:65], v[0:1] op_sel_hi:[1,0]
	v_pk_mul_f32 v[62:63], v[62:63], v[0:1] op_sel_hi:[1,0]
	v_pk_mul_f32 v[60:61], v[60:61], v[0:1] op_sel_hi:[1,0]
	v_pk_mul_f32 v[58:59], v[58:59], v[0:1] op_sel_hi:[1,0]
	v_pk_mul_f32 v[56:57], v[56:57], v[0:1] op_sel_hi:[1,0]
	v_pk_mul_f32 v[54:55], v[54:55], v[0:1] op_sel_hi:[1,0]
	v_pk_mul_f32 v[52:53], v[52:53], v[0:1] op_sel_hi:[1,0]
	v_pk_mul_f32 v[50:51], v[50:51], v[0:1] op_sel_hi:[1,0]
	v_pk_mul_f32 v[48:49], v[48:49], v[0:1] op_sel_hi:[1,0]
	v_pk_mul_f32 v[46:47], v[46:47], v[0:1] op_sel_hi:[1,0]
	v_pk_mul_f32 v[44:45], v[44:45], v[0:1] op_sel_hi:[1,0]
	v_pk_mul_f32 v[42:43], v[42:43], v[0:1] op_sel_hi:[1,0]
	v_pk_mul_f32 v[40:41], v[40:41], v[0:1] op_sel_hi:[1,0]
	v_pk_mul_f32 v[38:39], v[38:39], v[0:1] op_sel_hi:[1,0]
	v_pk_mul_f32 v[36:37], v[36:37], v[0:1] op_sel_hi:[1,0]
	v_pk_mul_f32 v[34:35], v[34:35], v[0:1] op_sel_hi:[1,0]
	v_pk_mul_f32 v[32:33], v[32:33], v[0:1] op_sel_hi:[1,0]
	v_pk_mul_f32 v[30:31], v[30:31], v[0:1] op_sel_hi:[1,0]
	v_pk_mul_f32 v[28:29], v[28:29], v[0:1] op_sel_hi:[1,0]
	v_pk_mul_f32 v[26:27], v[26:27], v[0:1] op_sel_hi:[1,0]
	v_pk_mul_f32 v[24:25], v[24:25], v[0:1] op_sel_hi:[1,0]
	v_pk_mul_f32 v[22:23], v[22:23], v[0:1] op_sel_hi:[1,0]
	v_pk_mul_f32 v[20:21], v[20:21], v[0:1] op_sel_hi:[1,0]
	v_pk_mul_f32 v[18:19], v[18:19], v[0:1] op_sel_hi:[1,0]
	v_pk_mul_f32 v[16:17], v[16:17], v[0:1] op_sel_hi:[1,0]
	v_pk_mul_f32 v[14:15], v[14:15], v[0:1] op_sel_hi:[1,0]
	v_pk_mul_f32 v[12:13], v[12:13], v[0:1] op_sel_hi:[1,0]
	v_pk_mul_f32 v[10:11], v[10:11], v[0:1] op_sel_hi:[1,0]
	v_pk_mul_f32 v[8:9], v[8:9], v[0:1] op_sel_hi:[1,0]
	v_pk_mul_f32 v[6:7], v[6:7], v[0:1] op_sel_hi:[1,0]
	v_pk_mul_f32 v[4:5], v[4:5], v[0:1] op_sel_hi:[1,0]
	v_pk_mul_f32 v[2:3], v[2:3], v[0:1] op_sel_hi:[1,0]
	v_sub_f32_e32 v182, v182, v146
	v_sub_f32_e32 v183, v183, v146
	v_sub_f32_e32 v184, v184, v146
	v_sub_f32_e32 v185, v185, v146
	v_sub_f32_e32 v186, v186, v146
	v_sub_f32_e32 v187, v187, v146
	v_sub_f32_e32 v192, v192, v146
	v_sub_f32_e32 v193, v193, v146
	v_sub_f32_e32 v206, v206, v146
	v_sub_f32_e32 v207, v207, v146
	v_sub_f32_e32 v188, v188, v146
	v_sub_f32_e32 v189, v189, v146
	v_pk_add_f32 v[190:191], v[190:191], v[146:147] op_sel_hi:[1,0] neg_lo:[0,1] neg_hi:[0,1]
	v_pk_add_f32 v[204:205], v[204:205], v[146:147] op_sel_hi:[1,0] neg_lo:[0,1] neg_hi:[0,1]
	v_pk_add_f32 v[208:209], v[208:209], v[146:147] op_sel_hi:[1,0] neg_lo:[0,1] neg_hi:[0,1]
	v_pk_add_f32 v[210:211], v[210:211], v[146:147] op_sel_hi:[1,0] neg_lo:[0,1] neg_hi:[0,1]
	v_pk_add_f32 v[212:213], v[212:213], v[146:147] op_sel_hi:[1,0] neg_lo:[0,1] neg_hi:[0,1]
	v_pk_add_f32 v[214:215], v[214:215], v[146:147] op_sel_hi:[1,0] neg_lo:[0,1] neg_hi:[0,1]
	v_pk_add_f32 v[216:217], v[216:217], v[146:147] op_sel_hi:[1,0] neg_lo:[0,1] neg_hi:[0,1]
	v_pk_add_f32 v[218:219], v[218:219], v[146:147] op_sel_hi:[1,0] neg_lo:[0,1] neg_hi:[0,1]
	v_pk_add_f32 v[220:221], v[220:221], v[146:147] op_sel_hi:[1,0] neg_lo:[0,1] neg_hi:[0,1]
	v_sub_f32_e32 v176, v176, v146
.LBB0_371:
	s_cmp_ge_u32 s27, s22
	s_cbranch_scc1 .Lqn_skip1
	s_add_i32 s99, s94, 64
	v_cmp_le_i32_e32 vcc, s99, v229
	s_cbranch_vccz .Lqn_skip1
	s_mov_b32 s99, 0x2400
	v_add3_u32 v148, v232, v238, s99
	ds_read_b128 v[114:117], v148
	ds_read_b128 v[118:121], v148 offset:4608
	ds_read_b128 v[122:125], v148 offset:32
	ds_read_b128 v[126:129], v148 offset:4640
	ds_read_b128 v[130:133], v148 offset:64
	ds_read_b128 v[134:137], v148 offset:4672
	ds_read_b128 v[138:141], v148 offset:96
	ds_read_b128 v[142:145], v148 offset:4704
	s_waitcnt lgkmcnt(7)
	v_mfma_f32_32x32x16_bf16 v[82:97], v[114:117], v[98:101], 0
	s_waitcnt lgkmcnt(6)
	v_mfma_f32_32x32x16_bf16 v[66:81], v[118:121], v[98:101], 0
	s_waitcnt lgkmcnt(5)
	v_mfma_f32_32x32x16_bf16 v[82:97], v[122:125], v[102:105], v[82:97]
	s_waitcnt lgkmcnt(4)
	v_mfma_f32_32x32x16_bf16 v[66:81], v[126:129], v[102:105], v[66:81]
	s_waitcnt lgkmcnt(3)
	v_mfma_f32_32x32x16_bf16 v[82:97], v[130:133], v[106:109], v[82:97]
	s_waitcnt lgkmcnt(2)
	v_mfma_f32_32x32x16_bf16 v[66:81], v[134:137], v[106:109], v[66:81]
	s_waitcnt lgkmcnt(1)
	v_mfma_f32_32x32x16_bf16 v[82:97], v[138:141], v[110:113], v[82:97]
	s_waitcnt lgkmcnt(0)
	v_mfma_f32_32x32x16_bf16 v[66:81], v[142:145], v[110:113], v[66:81]
.Lqn_skip1:
	v_exp_f32_e32 v114, v180
	v_exp_f32_e32 v115, v181
	v_exp_f32_e32 v116, v182
	v_exp_f32_e32 v117, v183
	v_exp_f32_e32 v118, v184
	v_exp_f32_e32 v119, v185
	v_exp_f32_e32 v120, v186
	v_exp_f32_e32 v121, v187
	v_cvt_pk_bf16_f32 v122, v114, v115
	v_cvt_pk_bf16_f32 v123, v116, v117
	v_cvt_pk_bf16_f32 v124, v118, v119
	v_cvt_pk_bf16_f32 v125, v120, v121
	ds_read_b128 v[130:133], v242 offset:9248
	v_exp_f32_e32 v126, v188
	s_waitcnt lgkmcnt(4)
	v_mfma_f32_32x32x16_bf16 v[50:65], v[162:165], v[122:125], v[50:65]
	v_exp_f32_e32 v127, v189
	v_exp_f32_e32 v128, v190
	v_exp_f32_e32 v129, v191
	v_exp_f32_e32 v162, v218
	v_cvt_pk_bf16_f32 v136, v126, v127
	v_exp_f32_e32 v163, v219
	v_cvt_pk_bf16_f32 v137, v128, v129
	s_waitcnt lgkmcnt(3)
	v_mfma_f32_32x32x16_bf16 v[34:49], v[158:161], v[122:125], v[34:49]
	v_exp_f32_e32 v158, v214
	v_exp_f32_e32 v159, v215
	v_exp_f32_e32 v160, v216
	v_exp_f32_e32 v161, v217
	v_exp_f32_e32 v164, v220
	v_exp_f32_e32 v165, v221
	v_pk_add_f32 v[114:115], v[114:115], 0 op_sel_hi:[1,0]
	s_waitcnt lgkmcnt(2)
	v_mfma_f32_32x32x16_bf16 v[18:33], v[154:157], v[122:125], v[18:33]
	v_exp_f32_e32 v154, v210
	v_exp_f32_e32 v155, v211
	v_exp_f32_e32 v156, v212
	v_exp_f32_e32 v157, v213
	v_pk_add_f32 v[114:115], v[116:117], v[114:115]
	s_nop 0
	v_pk_add_f32 v[114:115], v[118:119], v[114:115]
	s_waitcnt lgkmcnt(1)
	v_mfma_f32_32x32x16_bf16 v[2:17], v[150:153], v[122:125], v[2:17]
	v_exp_f32_e32 v122, v192
	v_exp_f32_e32 v123, v193
	v_exp_f32_e32 v124, v206
	v_exp_f32_e32 v125, v207
	v_exp_f32_e32 v150, v204
	v_cvt_pk_bf16_f32 v134, v122, v123
	v_exp_f32_e32 v151, v205
	v_cvt_pk_bf16_f32 v135, v124, v125
	v_exp_f32_e32 v152, v208
	v_exp_f32_e32 v153, v209
	s_waitcnt lgkmcnt(0)
	v_mfma_f32_32x32x16_bf16 v[50:65], v[130:133], v[134:137], v[50:65]
	ds_read_b128 v[130:133], v242 offset:13856
	v_add_f32_e64 v114, v120, v114
	v_add_f32_e64 v115, v121, v115
	v_add_f32_e64 v114, v122, v114
	v_add_f32_e64 v115, v123, v115
	v_pk_add_f32 v[114:115], v[124:125], v[114:115]
	s_waitcnt lgkmcnt(0)
	v_mfma_f32_32x32x16_bf16 v[34:49], v[130:133], v[134:137], v[34:49]
	ds_read_b128 v[130:133], v242 offset:18464
	v_add_f32_e64 v114, v126, v114
	v_add_f32_e64 v115, v127, v115
	v_add_f32_e64 v114, v128, v114
	v_add_f32_e64 v115, v129, v115
	v_pk_add_f32 v[114:115], v[150:151], v[114:115]
	s_waitcnt lgkmcnt(0)
	v_mfma_f32_32x32x16_bf16 v[18:33], v[130:133], v[134:137], v[18:33]
	ds_read_b128 v[130:133], v242 offset:23072
	ds_read_b128 v[138:141], v242 offset:9280
	v_add_f32_e64 v114, v152, v114
	v_add_f32_e64 v115, v153, v115
	v_add_f32_e64 v114, v154, v114
	v_add_f32_e64 v115, v155, v115
	v_pk_add_f32 v[114:115], v[156:157], v[114:115]
	s_waitcnt lgkmcnt(1)
	v_mfma_f32_32x32x16_bf16 v[2:17], v[130:133], v[134:137], v[2:17]
	ds_read_b128 v[134:137], v242 offset:13888
	v_cvt_pk_bf16_f32 v130, v150, v151
	v_cvt_pk_bf16_f32 v131, v152, v153
	v_cvt_pk_bf16_f32 v132, v154, v155
	v_cvt_pk_bf16_f32 v133, v156, v157
	v_pk_add_f32 v[114:115], v[158:159], v[114:115]
	s_waitcnt lgkmcnt(0)
	v_mfma_f32_32x32x16_bf16 v[34:49], v[134:137], v[130:133], v[34:49]
	ds_read_b128 v[134:137], v242 offset:18496
	v_add_f32_e64 v114, v160, v114
	v_add_f32_e64 v115, v161, v115
	v_add_f32_e64 v114, v162, v114
	v_add_f32_e64 v115, v163, v115
	v_pk_add_f32 v[114:115], v[164:165], v[114:115]
	v_mfma_f32_32x32x16_bf16 v[50:65], v[138:141], v[130:133], v[50:65]
	v_add_f32_e32 v114, v114, v115
	v_fmac_f32_e32 v114, v241, v0
	s_waitcnt lgkmcnt(0)
	v_mfma_f32_32x32x16_bf16 v[18:33], v[134:137], v[130:133], v[18:33]
	ds_read_b128 v[134:137], v242 offset:23104
	ds_read_b128 v[138:141], v242 offset:9312
	s_waitcnt lgkmcnt(1)
	v_mfma_f32_32x32x16_bf16 v[2:17], v[134:137], v[130:133], v[2:17]
	v_cvt_pk_bf16_f32 v130, v158, v159
	v_cvt_pk_bf16_f32 v131, v160, v161
	v_cvt_pk_bf16_f32 v132, v162, v163
	v_cvt_pk_bf16_f32 v133, v164, v165
	s_waitcnt lgkmcnt(0)
	s_nop 0
	v_mfma_f32_32x32x16_bf16 v[50:65], v[138:141], v[130:133], v[50:65]
	ds_read_b128 v[134:137], v242 offset:13920
	ds_read_b128 v[138:141], v242 offset:18528
	ds_read_b128 v[142:145], v242 offset:23136
	s_waitcnt lgkmcnt(2)
	v_mfma_f32_32x32x16_bf16 v[34:49], v[134:137], v[130:133], v[34:49]
	s_waitcnt lgkmcnt(1)
	v_mfma_f32_32x32x16_bf16 v[18:33], v[138:141], v[130:133], v[18:33]
	s_waitcnt lgkmcnt(0)
	v_mfma_f32_32x32x16_bf16 v[2:17], v[142:145], v[130:133], v[2:17]
	v_mov_b32_e32 v241, v114

.LBB0_375:
	s_cmp_ge_u32 s26, s25
	s_cbranch_scc1 .LBB0_378
	s_add_i32 s101, s26, 2
	s_bitcmp1_b32 s101, 0
	s_mov_b32 s98, 0x6c00
	s_cselect_b32 s98, 0xb400, s98
	s_lshl_b32 m0, s83, 4
	s_add_i32 s98, s98, m0
	v_mad_u64_u32 v[204:205], vcc, v252, s101, v[226:227]
	s_mov_b32 m0, s98
	v_mad_u64_u32 v[206:207], vcc, v252, s101, v[248:249]
	global_load_lds_dwordx4 v[204:205], off
	s_add_i32 m0, s98, 0x2000
	s_cmp_ge_u32 s83, 0x80
	global_load_lds_dwordx4 v[206:207], off
	s_cbranch_scc1 .Lpk_k2
	v_mad_u64_u32 v[208:209], vcc, v252, s101, v[250:251]
	s_add_i32 m0, s98, 0x4000
	s_nop 0
	global_load_lds_dwordx4 v[208:209], off
.Lpk_k2:
	s_add_i32 s100, s26, 3
	s_cmp_ge_u32 s100, s22
	s_cbranch_scc1 .LBB0_378
	s_lshl_b32 m0, s83, 4
	s_add_i32 s98, m0, 0x0
	v_mad_u64_u32 v[204:205], vcc, v245, s100, v[222:223]
	s_mov_b32 m0, s98
	s_cmp_lg_u32 s83, 0
	global_load_lds_dwordx4 v[204:205], off
	s_cbranch_scc1 .LBB0_378
	v_mad_u64_u32 v[206:207], vcc, v245, s100, v[224:225]
	s_add_i32 m0, s98, 0x2000
	s_nop 0
	global_load_lds_dwordx4 v[206:207], off
.LBB0_378:
	s_add_i32 s0, s94, 64
	v_cmp_le_i32_e32 vcc, s0, v229
	s_and_saveexec_b64 s[10:11], vcc
	s_cbranch_execz .LBB0_387
	s_mov_b32 s99, 0x4800
	s_bitcmp1_b32 s27, 0
	s_cselect_b32 s99, 0x9000, s99
	v_add3_u32 v242, v232, v233, s99
	ds_read_b128 v[162:165], v242 offset:9216
	ds_read_b128 v[158:161], v242 offset:13824
	ds_read_b128 v[154:157], v242 offset:18432
	ds_read_b128 v[150:153], v242 offset:23040
	s_movk_i32 s0, 0x7f
	v_add_u32_e32 v180, 64, v240
	v_add3_u32 v0, v236, v240, s0
	v_cmp_gt_i32_e32 vcc, s85, v180
	s_and_saveexec_b64 s[0:1], vcc
	s_xor_b64 s[0:1], exec, s[0:1]
	s_cbranch_execnz .LBB0_383
	s_andn2_saveexec_b64 s[0:1], s[0:1]
	s_cbranch_execnz .LBB0_384

.LBB0_382:
	v_mov_b32_e32 v0, v243
	v_mov_b32_e32 v146, v243
	s_nop 1
	v_permlane32_swap_b32_e32 v0, v146
	v_cmp_eq_u32_e32 vcc, v0, v243
	s_nop 1
	v_cndmask_b32_e32 v0, v0, v146, vcc
	v_max_f32_e32 v0, v0, v0
	v_max_f32_e32 v146, v243, v243
	v_max_f32_e32 v0, v146, v0
	v_cmp_lt_f32_e32 vcc, s92, v0
	s_nop 1
	v_cndmask_b32_e32 v146, 0, v0, vcc
	v_exp_f32_e64 v0, -v146
	v_add_f32_e32 v178, v178, v146
	v_sub_f32_e32 v180, v180, v146
	v_sub_f32_e32 v181, v181, v146
	v_pk_mul_f32 v[64:65], v[64:65], v[0:1] op_sel_hi:[1,0]
	v_pk_mul_f32 v[62:63], v[62:63], v[0:1] op_sel_hi:[1,0]
	v_pk_mul_f32 v[60:61], v[60:61], v[0:1] op_sel_hi:[1,0]
	v_pk_mul_f32 v[58:59], v[58:59], v[0:1] op_sel_hi:[1,0]
	v_pk_mul_f32 v[56:57], v[56:57], v[0:1] op_sel_hi:[1,0]
	v_pk_mul_f32 v[54:55], v[54:55], v[0:1] op_sel_hi:[1,0]
	v_pk_mul_f32 v[52:53], v[52:53], v[0:1] op_sel_hi:[1,0]
	v_pk_mul_f32 v[50:51], v[50:51], v[0:1] op_sel_hi:[1,0]
	v_pk_mul_f32 v[48:49], v[48:49], v[0:1] op_sel_hi:[1,0]
	v_pk_mul_f32 v[46:47], v[46:47], v[0:1] op_sel_hi:[1,0]
	v_pk_mul_f32 v[44:45], v[44:45], v[0:1] op_sel_hi:[1,0]
	v_pk_mul_f32 v[42:43], v[42:43], v[0:1] op_sel_hi:[1,0]
	v_pk_mul_f32 v[40:41], v[40:41], v[0:1] op_sel_hi:[1,0]
	v_pk_mul_f32 v[38:39], v[38:39], v[0:1] op_sel_hi:[1,0]
	v_pk_mul_f32 v[36:37], v[36:37], v[0:1] op_sel_hi:[1,0]
	v_pk_mul_f32 v[34:35], v[34:35], v[0:1] op_sel_hi:[1,0]
	v_pk_mul_f32 v[32:33], v[32:33], v[0:1] op_sel_hi:[1,0]
	v_pk_mul_f32 v[30:31], v[30:31], v[0:1] op_sel_hi:[1,0]
	v_pk_mul_f32 v[28:29], v[28:29], v[0:1] op_sel_hi:[1,0]
	v_pk_mul_f32 v[26:27], v[26:27], v[0:1] op_sel_hi:[1,0]
	v_pk_mul_f32 v[24:25], v[24:25], v[0:1] op_sel_hi:[1,0]
	v_pk_mul_f32 v[22:23], v[22:23], v[0:1] op_sel_hi:[1,0]
	v_pk_mul_f32 v[20:21], v[20:21], v[0:1] op_sel_hi:[1,0]
	v_pk_mul_f32 v[18:19], v[18:19], v[0:1] op_sel_hi:[1,0]
	v_pk_mul_f32 v[16:17], v[16:17], v[0:1] op_sel_hi:[1,0]
	v_pk_mul_f32 v[14:15], v[14:15], v[0:1] op_sel_hi:[1,0]
	v_pk_mul_f32 v[12:13], v[12:13], v[0:1] op_sel_hi:[1,0]
	v_pk_mul_f32 v[10:11], v[10:11], v[0:1] op_sel_hi:[1,0]
	v_pk_mul_f32 v[8:9], v[8:9], v[0:1] op_sel_hi:[1,0]
	v_pk_mul_f32 v[6:7], v[6:7], v[0:1] op_sel_hi:[1,0]
	v_pk_mul_f32 v[4:5], v[4:5], v[0:1] op_sel_hi:[1,0]
	v_pk_mul_f32 v[2:3], v[2:3], v[0:1] op_sel_hi:[1,0]
	v_sub_f32_e32 v182, v182, v146
	v_sub_f32_e32 v183, v183, v146
	v_sub_f32_e32 v184, v184, v146
	v_sub_f32_e32 v185, v185, v146
	v_sub_f32_e32 v186, v186, v146
	v_sub_f32_e32 v187, v187, v146
	v_sub_f32_e32 v192, v192, v146
	v_sub_f32_e32 v193, v193, v146
	v_sub_f32_e32 v206, v206, v146
	v_sub_f32_e32 v207, v207, v146
	v_sub_f32_e32 v188, v188, v146
	v_sub_f32_e32 v189, v189, v146
	v_pk_add_f32 v[190:191], v[190:191], v[146:147] op_sel_hi:[1,0] neg_lo:[0,1] neg_hi:[0,1]
	v_pk_add_f32 v[204:205], v[204:205], v[146:147] op_sel_hi:[1,0] neg_lo:[0,1] neg_hi:[0,1]
	v_pk_add_f32 v[208:209], v[208:209], v[146:147] op_sel_hi:[1,0] neg_lo:[0,1] neg_hi:[0,1]
	v_pk_add_f32 v[210:211], v[210:211], v[146:147] op_sel_hi:[1,0] neg_lo:[0,1] neg_hi:[0,1]
	v_pk_add_f32 v[212:213], v[212:213], v[146:147] op_sel_hi:[1,0] neg_lo:[0,1] neg_hi:[0,1]
	v_pk_add_f32 v[214:215], v[214:215], v[146:147] op_sel_hi:[1,0] neg_lo:[0,1] neg_hi:[0,1]
	v_pk_add_f32 v[216:217], v[216:217], v[146:147] op_sel_hi:[1,0] neg_lo:[0,1] neg_hi:[0,1]
	v_pk_add_f32 v[218:219], v[218:219], v[146:147] op_sel_hi:[1,0] neg_lo:[0,1] neg_hi:[0,1]
	v_pk_add_f32 v[220:221], v[220:221], v[146:147] op_sel_hi:[1,0] neg_lo:[0,1] neg_hi:[0,1]
	v_sub_f32_e32 v176, v176, v146
	s_branch .LBB0_386

.LBB0_386:
	s_add_i32 s99, s26, 2
	s_cmp_ge_u32 s99, s22
	s_cbranch_scc1 .Lqn_skip2
	s_add_i32 s99, s94, 128
	v_cmp_le_i32_e32 vcc, s99, v229
	s_cbranch_vccz .Lqn_skip2
	s_mov_b32 s99, 0x4800
	v_add3_u32 v148, v232, v238, s99
	ds_read_b128 v[114:117], v148
	ds_read_b128 v[118:121], v148 offset:4608
	ds_read_b128 v[122:125], v148 offset:32
	ds_read_b128 v[126:129], v148 offset:4640
	ds_read_b128 v[130:133], v148 offset:64
	ds_read_b128 v[134:137], v148 offset:4672
	ds_read_b128 v[138:141], v148 offset:96
	ds_read_b128 v[142:145], v148 offset:4704
	s_waitcnt lgkmcnt(7)
	v_mfma_f32_32x32x16_bf16 v[82:97], v[114:117], v[98:101], 0
	s_waitcnt lgkmcnt(6)
	v_mfma_f32_32x32x16_bf16 v[66:81], v[118:121], v[98:101], 0
	s_waitcnt lgkmcnt(5)
	v_mfma_f32_32x32x16_bf16 v[82:97], v[122:125], v[102:105], v[82:97]
	s_waitcnt lgkmcnt(4)
	v_mfma_f32_32x32x16_bf16 v[66:81], v[126:129], v[102:105], v[66:81]
	s_waitcnt lgkmcnt(3)
	v_mfma_f32_32x32x16_bf16 v[82:97], v[130:133], v[106:109], v[82:97]
	s_waitcnt lgkmcnt(2)
	v_mfma_f32_32x32x16_bf16 v[66:81], v[134:137], v[106:109], v[66:81]
	s_waitcnt lgkmcnt(1)
	v_mfma_f32_32x32x16_bf16 v[82:97], v[138:141], v[110:113], v[82:97]
	s_waitcnt lgkmcnt(0)
	v_mfma_f32_32x32x16_bf16 v[66:81], v[142:145], v[110:113], v[66:81]

.LBB0_388:
	s_cmp_ge_u32 s12, s22
	s_cbranch_scc1 .LBB0_391
	s_bitcmp1_b32 s12, 0
	s_mov_b32 s98, 0x6c00
	s_cselect_b32 s98, 0xb400, s98
	s_lshl_b32 m0, s83, 4
	s_add_i32 s98, s98, m0
	v_mad_u64_u32 v[204:205], vcc, v252, s12, v[226:227]
	s_mov_b32 m0, s98
	v_mad_u64_u32 v[206:207], vcc, v252, s12, v[248:249]
	global_load_lds_dwordx4 v[204:205], off
	s_add_i32 m0, s98, 0x2000
	s_cmp_ge_u32 s83, 0x80
	global_load_lds_dwordx4 v[206:207], off
	s_cbranch_scc1 .Lpk_k3
	v_mad_u64_u32 v[208:209], vcc, v252, s12, v[250:251]
	s_add_i32 m0, s98, 0x4000
	s_nop 0
	global_load_lds_dwordx4 v[208:209], off
.Lpk_k3:
	s_add_i32 s100, s26, 4
	s_cmp_ge_u32 s100, s22
	s_cbranch_scc1 .LBB0_391
	s_lshl_b32 m0, s83, 4
	s_add_i32 s98, m0, 0x2400
	v_mad_u64_u32 v[204:205], vcc, v245, s100, v[222:223]
	s_mov_b32 m0, s98
	s_cmp_lg_u32 s83, 0
	global_load_lds_dwordx4 v[204:205], off
	s_cbranch_scc1 .LBB0_391
	v_mad_u64_u32 v[206:207], vcc, v245, s100, v[224:225]
	s_add_i32 m0, s98, 0x2000
	s_nop 0
	global_load_lds_dwordx4 v[206:207], off
.LBB0_391:
	s_add_i32 s0, s94, 0x80
	v_cmp_le_i32_e32 vcc, s0, v229
	s_and_saveexec_b64 s[10:11], vcc
	s_cbranch_execz .LBB0_400
	s_mov_b32 s99, 0x4800
	s_bitcmp1_b32 s26, 0
	s_cselect_b32 s99, 0x9000, s99
	v_add3_u32 v242, v232, v233, s99
	ds_read_b128 v[162:165], v242 offset:9216
	ds_read_b128 v[158:161], v242 offset:13824
	ds_read_b128 v[154:157], v242 offset:18432
	ds_read_b128 v[150:153], v242 offset:23040
	v_add3_u32 v0, v236, v240, 63
	v_cmp_gt_i32_e32 vcc, s85, v240
	s_and_saveexec_b64 s[0:1], vcc
	s_xor_b64 s[0:1], exec, s[0:1]
	s_cbranch_execnz .LBB0_396
	s_andn2_saveexec_b64 s[0:1], s[0:1]
	s_cbranch_execnz .LBB0_397

.LBB0_395:
	v_mov_b32_e32 v0, v243
	s_nop 0
	v_mov_b32_e32 v146, v243
	s_nop 1
	v_permlane32_swap_b32_e32 v0, v146
	v_cmp_eq_u32_e32 vcc, v0, v243
	s_nop 1
	v_cndmask_b32_e32 v0, v0, v146, vcc
	v_max_f32_e32 v0, v0, v0
	v_max_f32_e32 v146, v243, v243
	v_max_f32_e32 v0, v146, v0
	v_cmp_lt_f32_e32 vcc, s92, v0
	s_nop 1
	v_cndmask_b32_e32 v146, 0, v0, vcc
	v_exp_f32_e64 v0, -v146
	v_add_f32_e32 v178, v178, v146
	v_sub_f32_e32 v180, v180, v146
	v_sub_f32_e32 v181, v181, v146
	v_pk_mul_f32 v[64:65], v[64:65], v[0:1] op_sel_hi:[1,0]
	v_pk_mul_f32 v[62:63], v[62:63], v[0:1] op_sel_hi:[1,0]
	v_pk_mul_f32 v[60:61], v[60:61], v[0:1] op_sel_hi:[1,0]
	v_pk_mul_f32 v[58:59], v[58:59], v[0:1] op_sel_hi:[1,0]
	v_pk_mul_f32 v[56:57], v[56:57], v[0:1] op_sel_hi:[1,0]
	v_pk_mul_f32 v[54:55], v[54:55], v[0:1] op_sel_hi:[1,0]
	v_pk_mul_f32 v[52:53], v[52:53], v[0:1] op_sel_hi:[1,0]
	v_pk_mul_f32 v[50:51], v[50:51], v[0:1] op_sel_hi:[1,0]
	v_pk_mul_f32 v[48:49], v[48:49], v[0:1] op_sel_hi:[1,0]
	v_pk_mul_f32 v[46:47], v[46:47], v[0:1] op_sel_hi:[1,0]
	v_pk_mul_f32 v[44:45], v[44:45], v[0:1] op_sel_hi:[1,0]
	v_pk_mul_f32 v[42:43], v[42:43], v[0:1] op_sel_hi:[1,0]
	v_pk_mul_f32 v[40:41], v[40:41], v[0:1] op_sel_hi:[1,0]
	v_pk_mul_f32 v[38:39], v[38:39], v[0:1] op_sel_hi:[1,0]
	v_pk_mul_f32 v[36:37], v[36:37], v[0:1] op_sel_hi:[1,0]
	v_pk_mul_f32 v[34:35], v[34:35], v[0:1] op_sel_hi:[1,0]
	v_pk_mul_f32 v[32:33], v[32:33], v[0:1] op_sel_hi:[1,0]
	v_pk_mul_f32 v[30:31], v[30:31], v[0:1] op_sel_hi:[1,0]
	v_pk_mul_f32 v[28:29], v[28:29], v[0:1] op_sel_hi:[1,0]
	v_pk_mul_f32 v[26:27], v[26:27], v[0:1] op_sel_hi:[1,0]
	v_pk_mul_f32 v[24:25], v[24:25], v[0:1] op_sel_hi:[1,0]
	v_pk_mul_f32 v[22:23], v[22:23], v[0:1] op_sel_hi:[1,0]
	v_pk_mul_f32 v[20:21], v[20:21], v[0:1] op_sel_hi:[1,0]
	v_pk_mul_f32 v[18:19], v[18:19], v[0:1] op_sel_hi:[1,0]
	v_pk_mul_f32 v[16:17], v[16:17], v[0:1] op_sel_hi:[1,0]
	v_pk_mul_f32 v[14:15], v[14:15], v[0:1] op_sel_hi:[1,0]
	v_pk_mul_f32 v[12:13], v[12:13], v[0:1] op_sel_hi:[1,0]
	v_pk_mul_f32 v[10:11], v[10:11], v[0:1] op_sel_hi:[1,0]
	v_pk_mul_f32 v[8:9], v[8:9], v[0:1] op_sel_hi:[1,0]
	v_pk_mul_f32 v[6:7], v[6:7], v[0:1] op_sel_hi:[1,0]
	v_pk_mul_f32 v[4:5], v[4:5], v[0:1] op_sel_hi:[1,0]
	v_pk_mul_f32 v[2:3], v[2:3], v[0:1] op_sel_hi:[1,0]
	v_sub_f32_e32 v182, v182, v146
	v_sub_f32_e32 v183, v183, v146
	v_sub_f32_e32 v184, v184, v146
	v_sub_f32_e32 v185, v185, v146
	v_sub_f32_e32 v186, v186, v146
	v_sub_f32_e32 v187, v187, v146
	v_sub_f32_e32 v192, v192, v146
	v_sub_f32_e32 v193, v193, v146
	v_sub_f32_e32 v206, v206, v146
	v_sub_f32_e32 v207, v207, v146
	v_sub_f32_e32 v188, v188, v146
	v_sub_f32_e32 v189, v189, v146
	v_pk_add_f32 v[190:191], v[190:191], v[146:147] op_sel_hi:[1,0] neg_lo:[0,1] neg_hi:[0,1]
	v_pk_add_f32 v[204:205], v[204:205], v[146:147] op_sel_hi:[1,0] neg_lo:[0,1] neg_hi:[0,1]
	v_pk_add_f32 v[208:209], v[208:209], v[146:147] op_sel_hi:[1,0] neg_lo:[0,1] neg_hi:[0,1]
	v_pk_add_f32 v[210:211], v[210:211], v[146:147] op_sel_hi:[1,0] neg_lo:[0,1] neg_hi:[0,1]
	v_pk_add_f32 v[212:213], v[212:213], v[146:147] op_sel_hi:[1,0] neg_lo:[0,1] neg_hi:[0,1]
	v_pk_add_f32 v[214:215], v[214:215], v[146:147] op_sel_hi:[1,0] neg_lo:[0,1] neg_hi:[0,1]
	v_pk_add_f32 v[216:217], v[216:217], v[146:147] op_sel_hi:[1,0] neg_lo:[0,1] neg_hi:[0,1]
	v_pk_add_f32 v[218:219], v[218:219], v[146:147] op_sel_hi:[1,0] neg_lo:[0,1] neg_hi:[0,1]
	v_pk_add_f32 v[220:221], v[220:221], v[146:147] op_sel_hi:[1,0] neg_lo:[0,1] neg_hi:[0,1]
	v_sub_f32_e32 v176, v176, v146
	s_branch .LBB0_399

.LBB0_399:
	s_cmp_ge_u32 s12, s22
	s_cbranch_scc1 .Lqn_skip3
	s_add_i32 s99, s94, 192
	v_cmp_le_i32_e32 vcc, s99, v229
	s_cbranch_vccz .Lqn_skip3
	s_mov_b32 s99, 0x0
	v_add3_u32 v148, v232, v238, s99
	ds_read_b128 v[114:117], v148
	ds_read_b128 v[118:121], v148 offset:4608
	ds_read_b128 v[122:125], v148 offset:32
	ds_read_b128 v[126:129], v148 offset:4640
	ds_read_b128 v[130:133], v148 offset:64
	ds_read_b128 v[134:137], v148 offset:4672
	ds_read_b128 v[138:141], v148 offset:96
	ds_read_b128 v[142:145], v148 offset:4704
	s_waitcnt lgkmcnt(7)
	v_mfma_f32_32x32x16_bf16 v[82:97], v[114:117], v[98:101], 0
	s_waitcnt lgkmcnt(6)
	v_mfma_f32_32x32x16_bf16 v[66:81], v[118:121], v[98:101], 0
	s_waitcnt lgkmcnt(5)
	v_mfma_f32_32x32x16_bf16 v[82:97], v[122:125], v[102:105], v[82:97]
	s_waitcnt lgkmcnt(4)
	v_mfma_f32_32x32x16_bf16 v[66:81], v[126:129], v[102:105], v[66:81]
	s_waitcnt lgkmcnt(3)
	v_mfma_f32_32x32x16_bf16 v[82:97], v[130:133], v[106:109], v[82:97]
	s_waitcnt lgkmcnt(2)
	v_mfma_f32_32x32x16_bf16 v[66:81], v[134:137], v[106:109], v[66:81]
	s_waitcnt lgkmcnt(1)
	v_mfma_f32_32x32x16_bf16 v[82:97], v[138:141], v[110:113], v[82:97]
	s_waitcnt lgkmcnt(0)
	v_mfma_f32_32x32x16_bf16 v[66:81], v[142:145], v[110:113], v[66:81]
.Lqn_skip3:
	s_nop 0
	v_exp_f32_e32 v114, v180
	v_exp_f32_e32 v115, v181
	v_exp_f32_e32 v116, v182
	v_exp_f32_e32 v117, v183
	v_exp_f32_e32 v118, v184
	v_exp_f32_e32 v119, v185
	v_exp_f32_e32 v120, v186
	v_exp_f32_e32 v121, v187
	v_cvt_pk_bf16_f32 v122, v114, v115
	v_cvt_pk_bf16_f32 v123, v116, v117
	v_cvt_pk_bf16_f32 v124, v118, v119
	v_cvt_pk_bf16_f32 v125, v120, v121
	ds_read_b128 v[130:133], v242 offset:9248
	v_exp_f32_e32 v126, v188
	s_waitcnt lgkmcnt(4)
	v_mfma_f32_32x32x16_bf16 v[50:65], v[162:165], v[122:125], v[50:65]
	v_exp_f32_e32 v127, v189
	v_exp_f32_e32 v128, v190
	v_exp_f32_e32 v129, v191
	v_exp_f32_e32 v162, v218
	v_cvt_pk_bf16_f32 v136, v126, v127
	v_exp_f32_e32 v163, v219
	v_cvt_pk_bf16_f32 v137, v128, v129
	s_waitcnt lgkmcnt(3)
	v_mfma_f32_32x32x16_bf16 v[34:49], v[158:161], v[122:125], v[34:49]
	v_exp_f32_e32 v158, v214
	v_exp_f32_e32 v159, v215
	v_exp_f32_e32 v160, v216
	v_exp_f32_e32 v161, v217
	v_exp_f32_e32 v164, v220
	v_exp_f32_e32 v165, v221
	v_pk_add_f32 v[114:115], v[114:115], 0 op_sel_hi:[1,0]
	s_waitcnt lgkmcnt(2)
	v_mfma_f32_32x32x16_bf16 v[18:33], v[154:157], v[122:125], v[18:33]
	v_exp_f32_e32 v154, v210
	v_exp_f32_e32 v155, v211
	v_exp_f32_e32 v156, v212
	v_exp_f32_e32 v157, v213
	v_pk_add_f32 v[114:115], v[116:117], v[114:115]
	s_nop 0
	v_pk_add_f32 v[114:115], v[118:119], v[114:115]
	s_waitcnt lgkmcnt(1)
	v_mfma_f32_32x32x16_bf16 v[2:17], v[150:153], v[122:125], v[2:17]
	v_exp_f32_e32 v122, v192
	v_exp_f32_e32 v123, v193
	v_exp_f32_e32 v124, v206
	v_exp_f32_e32 v125, v207
	v_exp_f32_e32 v150, v204
	v_cvt_pk_bf16_f32 v134, v122, v123
	v_exp_f32_e32 v151, v205
	v_cvt_pk_bf16_f32 v135, v124, v125
	v_exp_f32_e32 v152, v208
	v_exp_f32_e32 v153, v209
	s_waitcnt lgkmcnt(0)
	v_mfma_f32_32x32x16_bf16 v[50:65], v[130:133], v[134:137], v[50:65]
	ds_read_b128 v[130:133], v242 offset:13856
	v_add_f32_e64 v114, v120, v114
	v_add_f32_e64 v115, v121, v115
	v_add_f32_e64 v114, v122, v114
	v_add_f32_e64 v115, v123, v115
	v_pk_add_f32 v[114:115], v[124:125], v[114:115]
	s_waitcnt lgkmcnt(0)
	v_mfma_f32_32x32x16_bf16 v[34:49], v[130:133], v[134:137], v[34:49]
	ds_read_b128 v[130:133], v242 offset:18464
	v_add_f32_e64 v114, v126, v114
	v_add_f32_e64 v115, v127, v115
	v_add_f32_e64 v114, v128, v114
	v_add_f32_e64 v115, v129, v115
	v_pk_add_f32 v[114:115], v[150:151], v[114:115]
	s_waitcnt lgkmcnt(0)
	v_mfma_f32_32x32x16_bf16 v[18:33], v[130:133], v[134:137], v[18:33]
	ds_read_b128 v[130:133], v242 offset:23072
	ds_read_b128 v[138:141], v242 offset:9280
	v_add_f32_e64 v114, v152, v114
	v_add_f32_e64 v115, v153, v115
	v_add_f32_e64 v114, v154, v114
	v_add_f32_e64 v115, v155, v115
	v_pk_add_f32 v[114:115], v[156:157], v[114:115]
	s_waitcnt lgkmcnt(1)
	v_mfma_f32_32x32x16_bf16 v[2:17], v[130:133], v[134:137], v[2:17]
	ds_read_b128 v[134:137], v242 offset:13888
	v_cvt_pk_bf16_f32 v130, v150, v151
	v_cvt_pk_bf16_f32 v131, v152, v153
	v_cvt_pk_bf16_f32 v132, v154, v155
	v_cvt_pk_bf16_f32 v133, v156, v157
	v_pk_add_f32 v[114:115], v[158:159], v[114:115]
	s_waitcnt lgkmcnt(0)
	v_mfma_f32_32x32x16_bf16 v[34:49], v[134:137], v[130:133], v[34:49]
	ds_read_b128 v[134:137], v242 offset:18496
	v_add_f32_e64 v114, v160, v114
	v_add_f32_e64 v115, v161, v115
	v_add_f32_e64 v114, v162, v114
	v_add_f32_e64 v115, v163, v115
	v_pk_add_f32 v[114:115], v[164:165], v[114:115]
	v_mfma_f32_32x32x16_bf16 v[50:65], v[138:141], v[130:133], v[50:65]
	v_add_f32_e32 v114, v114, v115
	v_fmac_f32_e32 v114, v241, v0
	s_waitcnt lgkmcnt(0)
	v_mfma_f32_32x32x16_bf16 v[18:33], v[134:137], v[130:133], v[18:33]
	ds_read_b128 v[134:137], v242 offset:23104
	ds_read_b128 v[138:141], v242 offset:9312
	s_waitcnt lgkmcnt(1)
	v_mfma_f32_32x32x16_bf16 v[2:17], v[134:137], v[130:133], v[2:17]
	v_cvt_pk_bf16_f32 v130, v158, v159
	v_cvt_pk_bf16_f32 v131, v160, v161
	v_cvt_pk_bf16_f32 v132, v162, v163
	v_cvt_pk_bf16_f32 v133, v164, v165
	s_waitcnt lgkmcnt(0)
	s_nop 0
	v_mfma_f32_32x32x16_bf16 v[50:65], v[138:141], v[130:133], v[50:65]
	ds_read_b128 v[134:137], v242 offset:13920
	ds_read_b128 v[138:141], v242 offset:18528
	ds_read_b128 v[142:145], v242 offset:23136
	s_waitcnt lgkmcnt(2)
	v_mfma_f32_32x32x16_bf16 v[34:49], v[134:137], v[130:133], v[34:49]
	s_waitcnt lgkmcnt(1)
	v_mfma_f32_32x32x16_bf16 v[18:33], v[138:141], v[130:133], v[18:33]
	s_waitcnt lgkmcnt(0)
	v_mfma_f32_32x32x16_bf16 v[2:17], v[142:145], v[130:133], v[2:17]
	v_mov_b32_e32 v241, v114
